# weight-copy items: non-temporal (nt) hint on the streaming f32 source loads and bf16 output stores so they do not displace the attention K/V working set in L2
# baseline (speedup 1.0000x reference)
.LBB0_248:
	v_add_u32_e32 v58, v68, v69
	s_waitcnt vmcnt(0)
	ds_write2_b32 v58, v4, v5 offset1:1
	ds_write2_b32 v58, v6, v7 offset0:2 offset1:3
	v_add_u32_e32 v4, 0x420, v58
	ds_write2_b32 v4, v0, v1 offset1:1
	v_add_u32_e32 v0, 0x428, v58
	ds_write2_b32 v0, v2, v3 offset1:1
	v_add_u32_e32 v0, 0x840, v58
	ds_write2_b32 v0, v12, v13 offset1:1
	v_add_u32_e32 v0, 0x848, v58
	ds_write2_b32 v0, v14, v15 offset1:1
	v_add_u32_e32 v0, 0xc60, v58
	ds_write2_b32 v0, v8, v9 offset1:1
	v_add_u32_e32 v0, 0xc68, v58
	ds_write2_b32 v0, v10, v11 offset1:1
	v_add_u32_e32 v0, 0x1080, v58
	ds_write2_b32 v0, v20, v21 offset1:1
	v_add_u32_e32 v0, 0x1088, v58
	ds_write2_b32 v0, v22, v23 offset1:1
	v_add_u32_e32 v0, 0x14a0, v58
	ds_write2_b32 v0, v16, v17 offset1:1
	v_add_u32_e32 v0, 0x14a8, v58
	ds_write2_b32 v0, v18, v19 offset1:1
	v_add_u32_e32 v0, 0x18c0, v58
	ds_write2_b32 v0, v28, v29 offset1:1
	v_add_u32_e32 v0, 0x18c8, v58
	ds_write2_b32 v0, v30, v31 offset1:1
	v_add_u32_e32 v0, 0x1ce0, v58
	ds_write2_b32 v0, v24, v25 offset1:1
	v_add_u32_e32 v0, 0x1ce8, v58
	ds_write2_b32 v0, v26, v27 offset1:1
	s_waitcnt lgkmcnt(0)
	ds_read2_b32 v[4:5], v71 offset0:33 offset1:41
	ds_read2_b32 v[6:7], v71 offset1:8
	ds_read2_b32 v[8:9], v71 offset0:66 offset1:74
	ds_read2_b32 v[10:11], v71 offset0:99 offset1:107
	ds_read2_b32 v[12:13], v71 offset0:132 offset1:140
	ds_read2_b32 v[14:15], v71 offset0:165 offset1:173
	ds_read2_b32 v[16:17], v71 offset0:198 offset1:206
	ds_read2_b32 v[18:19], v71 offset0:231 offset1:239
	v_add_u32_e32 v22, s4, v32
	s_ashr_i32 s29, s28, 31
	v_ashrrev_i32_e32 v23, 31, v22
	v_lshl_add_u64 v[20:21], s[28:29], 1, v[56:57]
	v_lshlrev_b64 v[22:23], 11, v[22:23]
	s_waitcnt lgkmcnt(6)
	v_cvt_pk_bf16_f32 v0, v6, v4
	s_waitcnt lgkmcnt(4)
	v_cvt_pk_bf16_f32 v1, v8, v10
	s_waitcnt lgkmcnt(2)
	v_cvt_pk_bf16_f32 v2, v12, v14
	s_waitcnt lgkmcnt(0)
	v_cvt_pk_bf16_f32 v3, v16, v18
	v_lshl_add_u64 v[22:23], v[20:21], 0, v[22:23]
	v_add_u32_e32 v4, s4, v34
	global_store_dwordx4 v[22:23], v[0:3], off nt
	s_nop 1
	v_cvt_pk_bf16_f32 v0, v7, v5
	v_ashrrev_i32_e32 v5, 31, v4
	v_cvt_pk_bf16_f32 v1, v9, v11
	v_cvt_pk_bf16_f32 v2, v13, v15
	v_cvt_pk_bf16_f32 v3, v17, v19
	v_lshlrev_b64 v[4:5], 11, v[4:5]
	ds_read2_b32 v[6:7], v71 offset0:16 offset1:24
	ds_read2_b32 v[8:9], v71 offset0:49 offset1:57
	ds_read2_b32 v[10:11], v71 offset0:82 offset1:90
	ds_read2_b32 v[12:13], v71 offset0:115 offset1:123
	ds_read2_b32 v[14:15], v71 offset0:148 offset1:156
	ds_read2_b32 v[16:17], v71 offset0:181 offset1:189
	ds_read2_b32 v[18:19], v71 offset0:214 offset1:222
	ds_read2_b32 v[22:23], v71 offset0:247 offset1:255
	v_lshl_add_u64 v[4:5], v[20:21], 0, v[4:5]
	global_store_dwordx4 v[4:5], v[0:3], off nt
	v_add_u32_e32 v4, s4, v36
	v_ashrrev_i32_e32 v5, 31, v4
	v_lshlrev_b64 v[4:5], 11, v[4:5]
	s_waitcnt lgkmcnt(6)
	v_cvt_pk_bf16_f32 v0, v6, v8
	s_waitcnt lgkmcnt(4)
	v_cvt_pk_bf16_f32 v1, v10, v12
	s_waitcnt lgkmcnt(2)
	v_cvt_pk_bf16_f32 v2, v14, v16
	s_waitcnt lgkmcnt(0)
	v_cvt_pk_bf16_f32 v3, v18, v22
	v_lshl_add_u64 v[4:5], v[20:21], 0, v[4:5]
	global_store_dwordx4 v[4:5], v[0:3], off nt
	v_add_u32_e32 v4, s4, v38
	v_ashrrev_i32_e32 v5, 31, v4
	v_lshlrev_b64 v[4:5], 11, v[4:5]
	v_cvt_pk_bf16_f32 v0, v7, v9
	v_cvt_pk_bf16_f32 v1, v11, v13
	v_cvt_pk_bf16_f32 v2, v15, v17
	v_cvt_pk_bf16_f32 v3, v19, v23
	v_lshl_add_u64 v[4:5], v[20:21], 0, v[4:5]
	global_store_dwordx4 v[4:5], v[0:3], off nt
	s_waitcnt lgkmcnt(0)

.LBB0_250:
	s_add_i32 s36, s50, s0
	s_and_b64 vcc, exec, s[62:63]
	s_mov_b64 s[0:1], -1
	s_cbranch_vccz .LBB0_297
	s_add_i32 s4, s36, 0xffffee00
	s_cmpk_gt_i32 s36, 0x147f
	s_cbranch_scc0 .LBB0_277
	s_and_b32 s28, s4, 0x7fffffc0
	s_lshl_b32 s0, s36, 5
	s_add_i32 s34, s28, 0xfffffd80
	s_and_b32 s5, s0, 0x7e0
	s_cmpk_lt_u32 s5, 0x600
	s_movk_i32 s0, 0xfa00
	s_cselect_b32 s0, 0x680, s0
	s_cmpk_gt_u32 s5, 0x47f
	v_or_b32_e32 v0, s5, v67
	s_cselect_b32 s0, s0, 0x200
	v_add_u32_e32 v64, s0, v0
	v_cmp_lt_i32_e32 vcc, -1, v64
	v_add_u32_e32 v58, s34, v32
	v_lshl_add_u64 v[60:61], v[64:65], 2, s[22:23]
	v_mov_b32_e32 v0, 0
	v_mov_b32_e32 v12, 0
	v_mov_b32_e32 v13, 0
	v_mov_b32_e32 v14, 0
	v_mov_b32_e32 v15, 0
	s_and_saveexec_b64 s[0:1], vcc
	s_cbranch_execz .LBB0_254
	s_movk_i32 s6, 0x3260
	v_mad_i64_i32 v[2:3], s[6:7], v58, s6, v[60:61]
	global_load_dwordx4 v[12:15], v[2:3], off nt
.LBB0_254:
	s_or_b64 exec, exec, s[0:1]
	v_mov_b32_e32 v1, 0
	v_mov_b32_e32 v2, 0
	v_mov_b32_e32 v3, 0
	s_and_saveexec_b64 s[0:1], vcc
	s_cbranch_execz .LBB0_256
	v_add_u32_e32 v0, 8, v58
	s_movk_i32 s6, 0x3260
	v_mad_i64_i32 v[0:1], s[6:7], v0, s6, v[60:61]
	global_load_dwordx4 v[0:3], v[0:1], off nt
.LBB0_256:
	s_or_b64 exec, exec, s[0:1]
	v_mov_b32_e32 v4, 0
	v_mov_b32_e32 v20, 0
	v_mov_b32_e32 v21, 0
	v_mov_b32_e32 v22, 0
	v_mov_b32_e32 v23, 0
	s_and_saveexec_b64 s[0:1], vcc
	s_cbranch_execz .LBB0_258
	v_add_u32_e32 v5, 16, v58
	s_movk_i32 s6, 0x3260
	v_mad_i64_i32 v[6:7], s[6:7], v5, s6, v[60:61]
	global_load_dwordx4 v[20:23], v[6:7], off nt
.LBB0_258:
	s_or_b64 exec, exec, s[0:1]
	v_mov_b32_e32 v5, 0
	v_mov_b32_e32 v6, 0
	v_mov_b32_e32 v7, 0
	s_and_saveexec_b64 s[0:1], vcc
	s_cbranch_execz .LBB0_260
	v_add_u32_e32 v4, 24, v58
	s_movk_i32 s6, 0x3260
	v_mad_i64_i32 v[4:5], s[6:7], v4, s6, v[60:61]
	global_load_dwordx4 v[4:7], v[4:5], off nt
.LBB0_260:
	s_or_b64 exec, exec, s[0:1]
	v_mov_b32_e32 v8, 0
	v_mov_b32_e32 v24, 0
	v_mov_b32_e32 v25, 0
	v_mov_b32_e32 v26, 0
	v_mov_b32_e32 v27, 0
	s_and_saveexec_b64 s[0:1], vcc
	s_cbranch_execz .LBB0_262
	v_add_u32_e32 v9, 32, v58
	s_movk_i32 s6, 0x3260
	v_mad_i64_i32 v[10:11], s[6:7], v9, s6, v[60:61]
	global_load_dwordx4 v[24:27], v[10:11], off nt
.LBB0_262:
	s_or_b64 exec, exec, s[0:1]
	v_mov_b32_e32 v9, 0
	v_mov_b32_e32 v10, 0
	v_mov_b32_e32 v11, 0
	s_and_saveexec_b64 s[0:1], vcc
	s_cbranch_execz .LBB0_264
	v_add_u32_e32 v8, 40, v58
	s_movk_i32 s6, 0x3260
	v_mad_i64_i32 v[8:9], s[6:7], v8, s6, v[60:61]
	global_load_dwordx4 v[8:11], v[8:9], off nt
.LBB0_264:
	s_or_b64 exec, exec, s[0:1]
	v_mov_b32_e32 v16, 0
	v_mov_b32_e32 v28, 0
	v_mov_b32_e32 v29, 0
	v_mov_b32_e32 v30, 0
	v_mov_b32_e32 v31, 0
	s_and_saveexec_b64 s[0:1], vcc
	s_cbranch_execz .LBB0_266
	v_add_u32_e32 v17, 48, v58
	s_movk_i32 s6, 0x3260
	v_mad_i64_i32 v[18:19], s[6:7], v17, s6, v[60:61]
	global_load_dwordx4 v[28:31], v[18:19], off nt
.LBB0_266:
	s_or_b64 exec, exec, s[0:1]
	v_mov_b32_e32 v17, 0
	v_mov_b32_e32 v18, 0
	v_mov_b32_e32 v19, 0
	s_and_saveexec_b64 s[0:1], vcc
	s_cbranch_execz .LBB0_268
	v_add_u32_e32 v16, 56, v58
	s_movk_i32 s6, 0x3260
	v_mad_i64_i32 v[16:17], s[6:7], v16, s6, v[60:61]
	global_load_dwordx4 v[16:19], v[16:17], off nt

.LBB0_276:
	v_mov_b32_e32 v61, v0
	v_pk_mul_f32 v[4:5], v[28:29], v[60:61] op_sel_hi:[1,0]
	v_add_u32_e32 v3, 0x1080, v2
	v_pk_mul_f32 v[0:1], v[30:31], v[60:61] op_sel_hi:[1,0]
	ds_write2_b32 v3, v4, v5 offset1:1
	v_add_u32_e32 v3, 0x1088, v2
	ds_write2_b32 v3, v0, v1 offset1:1
	v_pk_mul_f32 v[0:1], v[16:17], v[60:61] op_sel:[0,1]
	v_add_u32_e32 v3, 0x14a0, v2
	ds_write2_b32 v3, v0, v1 offset1:1
	v_pk_mul_f32 v[0:1], v[18:19], v[60:61] op_sel:[0,1]
	v_add_u32_e32 v2, 0x14a8, v2
	ds_write2_b32 v2, v0, v1 offset1:1
	s_waitcnt lgkmcnt(0)
	ds_read2_b32 v[6:7], v71 offset0:33 offset1:41
	ds_read2_b32 v[8:9], v71 offset1:8
	ds_read2_b32 v[10:11], v71 offset0:66 offset1:74
	ds_read2_b32 v[12:13], v71 offset0:99 offset1:107
	ds_read2_b32 v[14:15], v71 offset0:132 offset1:140
	ds_read2_b32 v[16:17], v71 offset0:165 offset1:173
	ds_read2_b32 v[18:19], v71 offset0:198 offset1:206
	ds_read2_b32 v[20:21], v71 offset0:231 offset1:239
	v_add_u32_e32 v22, s5, v32
	v_ashrrev_i32_e32 v23, 31, v22
	v_lshl_add_u64 v[4:5], s[34:35], 1, v[48:49]
	v_lshlrev_b64 v[22:23], 11, v[22:23]
	s_waitcnt lgkmcnt(6)
	v_cvt_pk_bf16_f32 v0, v8, v6
	s_waitcnt lgkmcnt(4)
	v_cvt_pk_bf16_f32 v1, v10, v12
	s_waitcnt lgkmcnt(2)
	v_cvt_pk_bf16_f32 v2, v14, v16
	s_waitcnt lgkmcnt(0)
	v_cvt_pk_bf16_f32 v3, v18, v20
	v_lshl_add_u64 v[22:23], v[4:5], 0, v[22:23]
	v_add_u32_e32 v6, s5, v34
	global_store_dwordx4 v[22:23], v[0:3], off nt
	v_add_u32_e32 v22, s5, v36
	v_ashrrev_i32_e32 v23, 31, v22
	v_cvt_pk_bf16_f32 v0, v9, v7
	v_ashrrev_i32_e32 v7, 31, v6
	v_lshlrev_b64 v[6:7], 11, v[6:7]
	v_cvt_pk_bf16_f32 v1, v11, v13
	v_cvt_pk_bf16_f32 v2, v15, v17
	v_cvt_pk_bf16_f32 v3, v19, v21
	v_lshl_add_u64 v[6:7], v[4:5], 0, v[6:7]
	global_store_dwordx4 v[6:7], v[0:3], off nt
	ds_read2_b32 v[6:7], v71 offset0:16 offset1:24
	ds_read2_b32 v[8:9], v71 offset0:49 offset1:57
	ds_read2_b32 v[10:11], v71 offset0:82 offset1:90
	ds_read2_b32 v[12:13], v71 offset0:115 offset1:123
	ds_read2_b32 v[14:15], v71 offset0:148 offset1:156
	ds_read2_b32 v[16:17], v71 offset0:181 offset1:189
	ds_read2_b32 v[18:19], v71 offset0:214 offset1:222
	ds_read2_b32 v[20:21], v71 offset0:247 offset1:255
	v_lshlrev_b64 v[22:23], 11, v[22:23]
	s_waitcnt lgkmcnt(6)
	v_cvt_pk_bf16_f32 v0, v6, v8
	s_waitcnt lgkmcnt(4)
	v_cvt_pk_bf16_f32 v1, v10, v12
	s_waitcnt lgkmcnt(2)
	v_cvt_pk_bf16_f32 v2, v14, v16
	s_waitcnt lgkmcnt(0)
	v_cvt_pk_bf16_f32 v3, v18, v20
	v_lshl_add_u64 v[22:23], v[4:5], 0, v[22:23]
	v_add_u32_e32 v6, s5, v38
	global_store_dwordx4 v[22:23], v[0:3], off nt
	s_mov_b64 s[0:1], 0
	s_nop 0
	v_cvt_pk_bf16_f32 v0, v7, v9
	v_ashrrev_i32_e32 v7, 31, v6
	v_lshlrev_b64 v[6:7], 11, v[6:7]
	v_cvt_pk_bf16_f32 v1, v11, v13
	v_cvt_pk_bf16_f32 v2, v15, v17
	v_cvt_pk_bf16_f32 v3, v19, v21
	v_lshl_add_u64 v[4:5], v[4:5], 0, v[6:7]
	global_store_dwordx4 v[4:5], v[0:3], off nt
	s_waitcnt lgkmcnt(0)
.LBB0_277:
	s_and_b64 vcc, exec, s[0:1]
	s_cbranch_vccz .LBB0_296
	s_mul_hi_i32 s0, s4, 0x66666667
	s_lshr_b32 s1, s0, 31
	s_ashr_i32 s0, s0, 4
	s_add_i32 s0, s0, s1
	s_mul_i32 s1, s0, 40
	s_sub_i32 s1, s4, s1
	s_lshl_b32 s4, s1, 5
	s_lshl_b32 s28, s0, 6
	v_or_b32_e32 v0, s4, v67
	s_movk_i32 s0, 0x498
	v_add_u32_e32 v2, 0x800, v0
	v_cmp_gt_u32_e32 vcc, s0, v0
	s_movk_i32 s0, 0x480
	v_add_u32_e32 v1, 0x680, v0
	v_cndmask_b32_e32 v2, -1, v2, vcc
	v_cmp_gt_i32_e32 vcc, s0, v0
	v_add_u32_e32 v58, s28, v32
	v_mov_b32_e32 v24, 0
	v_cndmask_b32_e32 v64, v2, v1, vcc
	v_cmp_lt_i32_e32 vcc, -1, v64
	v_lshl_add_u64 v[60:61], v[64:65], 2, s[22:23]
	v_mov_b32_e32 v28, 0
	v_mov_b32_e32 v29, 0
	v_mov_b32_e32 v30, 0
	v_mov_b32_e32 v31, 0
	s_and_saveexec_b64 s[0:1], vcc
	s_cbranch_execz .LBB0_280
	s_movk_i32 s5, 0x3260
	v_mad_i64_i32 v[0:1], s[6:7], v58, s5, v[60:61]
	global_load_dwordx4 v[28:31], v[0:1], off nt
.LBB0_280:
	s_or_b64 exec, exec, s[0:1]
	v_mov_b32_e32 v25, 0
	v_mov_b32_e32 v26, 0
	v_mov_b32_e32 v27, 0
	s_and_saveexec_b64 s[0:1], vcc
	s_cbranch_execz .LBB0_282
	v_add_u32_e32 v0, 8, v58
	s_movk_i32 s5, 0x3260
	v_mad_i64_i32 v[0:1], s[6:7], v0, s5, v[60:61]
	global_load_dwordx4 v[24:27], v[0:1], off nt
.LBB0_282:
	s_or_b64 exec, exec, s[0:1]
	v_mov_b32_e32 v16, 0
	v_mov_b32_e32 v20, 0
	v_mov_b32_e32 v21, 0
	v_mov_b32_e32 v22, 0
	v_mov_b32_e32 v23, 0
	s_and_saveexec_b64 s[0:1], vcc
	s_cbranch_execz .LBB0_284
	v_add_u32_e32 v0, 16, v58
	s_movk_i32 s5, 0x3260
	v_mad_i64_i32 v[0:1], s[6:7], v0, s5, v[60:61]
	global_load_dwordx4 v[20:23], v[0:1], off nt
.LBB0_284:
	s_or_b64 exec, exec, s[0:1]
	v_mov_b32_e32 v17, 0
	v_mov_b32_e32 v18, 0
	v_mov_b32_e32 v19, 0
	s_and_saveexec_b64 s[0:1], vcc
	s_cbranch_execz .LBB0_286
	v_add_u32_e32 v0, 24, v58
	s_movk_i32 s5, 0x3260
	v_mad_i64_i32 v[0:1], s[6:7], v0, s5, v[60:61]
	global_load_dwordx4 v[16:19], v[0:1], off nt
.LBB0_286:
	s_or_b64 exec, exec, s[0:1]
	v_mov_b32_e32 v8, 0
	v_mov_b32_e32 v12, 0
	v_mov_b32_e32 v13, 0
	v_mov_b32_e32 v14, 0
	v_mov_b32_e32 v15, 0
	s_and_saveexec_b64 s[0:1], vcc
	s_cbranch_execz .LBB0_288
	v_add_u32_e32 v0, 32, v58
	s_movk_i32 s5, 0x3260
	v_mad_i64_i32 v[0:1], s[6:7], v0, s5, v[60:61]
	global_load_dwordx4 v[12:15], v[0:1], off nt
.LBB0_288:
	s_or_b64 exec, exec, s[0:1]
	v_mov_b32_e32 v9, 0
	v_mov_b32_e32 v10, 0
	v_mov_b32_e32 v11, 0
	s_and_saveexec_b64 s[0:1], vcc
	s_cbranch_execz .LBB0_290
	v_add_u32_e32 v0, 40, v58
	s_movk_i32 s5, 0x3260
	v_mad_i64_i32 v[0:1], s[6:7], v0, s5, v[60:61]
	global_load_dwordx4 v[8:11], v[0:1], off nt
.LBB0_290:
	s_or_b64 exec, exec, s[0:1]
	v_mov_b32_e32 v0, 0
	v_mov_b32_e32 v4, 0
	v_mov_b32_e32 v5, 0
	v_mov_b32_e32 v6, 0
	v_mov_b32_e32 v7, 0
	s_and_saveexec_b64 s[0:1], vcc
	s_cbranch_execz .LBB0_292
	v_add_u32_e32 v1, 48, v58
	s_movk_i32 s5, 0x3260
	v_mad_i64_i32 v[2:3], s[6:7], v1, s5, v[60:61]
	global_load_dwordx4 v[4:7], v[2:3], off nt
.LBB0_292:
	s_or_b64 exec, exec, s[0:1]
	v_mov_b32_e32 v1, 0
	v_mov_b32_e32 v2, 0
	v_mov_b32_e32 v3, 0
	s_and_saveexec_b64 s[0:1], vcc
	s_cbranch_execz .LBB0_294
	v_add_u32_e32 v0, 56, v58
	s_movk_i32 s5, 0x3260
	v_mad_i64_i32 v[0:1], s[6:7], v0, s5, v[60:61]
	global_load_dwordx4 v[0:3], v[0:1], off nt

.LBB0_298:
	s_cmpk_gt_i32 s36, 0x1ff
	s_mov_b64 s[0:1], -1
	s_cbranch_scc0 .LBB0_312
	s_lshl_b32 s4, s36, 5
	s_cmpk_gt_u32 s36, 0x9ff
	s_cbranch_scc0 .LBB0_301
	s_lshl_b32 s0, s36, 1
	s_and_b32 s0, s0, 0x7fffffc0
	s_add_i32 s34, s0, 0xffffec00
	s_and_b32 s0, s4, 0x3e0
	v_or_b32_e32 v1, s0, v67
	v_add_u32_e32 v0, s34, v32
	v_lshlrev_b32_e32 v64, 2, v1
	v_ashrrev_i32_e32 v1, 31, v0
	v_lshl_add_u64 v[2:3], s[46:47], 0, v[64:65]
	v_lshlrev_b64 v[0:1], 12, v[0:1]
	v_lshl_add_u64 v[28:29], v[2:3], 0, v[0:1]
	s_mov_b32 s1, 0x8000
	v_add_co_u32_e32 v4, vcc, s1, v28
	global_load_dwordx4 v[0:3], v[28:29], off nt
	s_nop 0
	v_addc_co_u32_e32 v5, vcc, 0, v29, vcc
	s_mov_b32 s1, 0x10000
	global_load_dwordx4 v[4:7], v[4:5], off nt
	v_add_co_u32_e32 v8, vcc, s1, v28
	s_mov_b32 s1, 0x18000
	s_nop 0
	v_addc_co_u32_e32 v9, vcc, 0, v29, vcc
	global_load_dwordx4 v[8:11], v[8:9], off nt
	v_add_co_u32_e32 v12, vcc, s1, v28
	s_mov_b32 s1, 0x20000
	s_nop 0
	v_addc_co_u32_e32 v13, vcc, 0, v29, vcc
	global_load_dwordx4 v[12:15], v[12:13], off nt
	v_add_co_u32_e32 v16, vcc, s1, v28
	s_mov_b32 s1, 0x28000
	s_nop 0
	v_addc_co_u32_e32 v17, vcc, 0, v29, vcc
	global_load_dwordx4 v[16:19], v[16:17], off nt
	v_add_co_u32_e32 v20, vcc, s1, v28
	s_mov_b32 s1, 0x30000
	s_nop 0
	v_addc_co_u32_e32 v21, vcc, 0, v29, vcc
	global_load_dwordx4 v[20:23], v[20:21], off nt
	v_add_co_u32_e32 v24, vcc, s1, v28
	s_mov_b32 s1, 0x38000
	s_nop 0
	v_addc_co_u32_e32 v25, vcc, 0, v29, vcc
	global_load_dwordx4 v[24:27], v[24:25], off nt
	v_add_co_u32_e32 v28, vcc, s1, v28
	v_add_u32_e32 v58, v68, v69
	s_nop 0
	v_addc_co_u32_e32 v29, vcc, 0, v29, vcc
	global_load_dwordx4 v[28:31], v[28:29], off nt
	s_waitcnt vmcnt(7)
	ds_write2_b32 v58, v0, v1 offset1:1
	ds_write2_b32 v58, v2, v3 offset0:2 offset1:3
	v_add_u32_e32 v0, 0x420, v58
	s_waitcnt vmcnt(6)
	ds_write2_b32 v0, v4, v5 offset1:1
	v_add_u32_e32 v0, 0x428, v58
	ds_write2_b32 v0, v6, v7 offset1:1
	v_add_u32_e32 v0, 0x840, v58
	s_waitcnt vmcnt(5)
	ds_write2_b32 v0, v8, v9 offset1:1
	v_add_u32_e32 v0, 0x848, v58
	ds_write2_b32 v0, v10, v11 offset1:1
	v_add_u32_e32 v0, 0xc60, v58
	s_waitcnt vmcnt(4)
	ds_write2_b32 v0, v12, v13 offset1:1
	v_add_u32_e32 v0, 0xc68, v58
	ds_write2_b32 v0, v14, v15 offset1:1
	v_add_u32_e32 v0, 0x1080, v58
	s_waitcnt vmcnt(3)
	ds_write2_b32 v0, v16, v17 offset1:1
	v_add_u32_e32 v0, 0x1088, v58
	ds_write2_b32 v0, v18, v19 offset1:1
	v_add_u32_e32 v0, 0x14a0, v58
	s_waitcnt vmcnt(2)
	ds_write2_b32 v0, v20, v21 offset1:1
	v_add_u32_e32 v0, 0x14a8, v58
	ds_write2_b32 v0, v22, v23 offset1:1
	v_add_u32_e32 v0, 0x18c0, v58
	v_add_u32_e32 v22, s0, v32
	v_ashrrev_i32_e32 v23, 31, v22
	s_waitcnt vmcnt(1)
	ds_write2_b32 v0, v24, v25 offset1:1
	v_add_u32_e32 v0, 0x18c8, v58
	ds_write2_b32 v0, v26, v27 offset1:1
	v_add_u32_e32 v0, 0x1ce0, v58
	v_lshlrev_b64 v[22:23], 13, v[22:23]
	s_waitcnt vmcnt(0)
	ds_write2_b32 v0, v28, v29 offset1:1
	v_add_u32_e32 v0, 0x1ce8, v58
	ds_write2_b32 v0, v30, v31 offset1:1
	s_waitcnt lgkmcnt(0)
	ds_read2_b32 v[6:7], v71 offset0:33 offset1:41
	ds_read2_b32 v[8:9], v71 offset1:8
	ds_read2_b32 v[10:11], v71 offset0:66 offset1:74
	ds_read2_b32 v[12:13], v71 offset0:99 offset1:107
	ds_read2_b32 v[14:15], v71 offset0:132 offset1:140
	ds_read2_b32 v[16:17], v71 offset0:165 offset1:173
	ds_read2_b32 v[18:19], v71 offset0:198 offset1:206
	ds_read2_b32 v[20:21], v71 offset0:231 offset1:239
	v_lshl_add_u64 v[0:1], s[34:35], 1, v[52:53]
	s_waitcnt lgkmcnt(6)
	v_cvt_pk_bf16_f32 v2, v8, v6
	s_waitcnt lgkmcnt(4)
	v_cvt_pk_bf16_f32 v3, v10, v12
	s_waitcnt lgkmcnt(2)
	v_cvt_pk_bf16_f32 v4, v14, v16
	s_waitcnt lgkmcnt(0)
	v_cvt_pk_bf16_f32 v5, v18, v20
	v_lshl_add_u64 v[22:23], v[0:1], 0, v[22:23]
	v_add_u32_e32 v6, s0, v34
	global_store_dwordx4 v[22:23], v[2:5], off nt
	v_add_u32_e32 v22, s0, v36
	v_ashrrev_i32_e32 v23, 31, v22
	v_cvt_pk_bf16_f32 v2, v9, v7
	v_ashrrev_i32_e32 v7, 31, v6
	v_lshlrev_b64 v[6:7], 13, v[6:7]
	v_cvt_pk_bf16_f32 v3, v11, v13
	v_cvt_pk_bf16_f32 v4, v15, v17
	v_cvt_pk_bf16_f32 v5, v19, v21
	v_lshl_add_u64 v[6:7], v[0:1], 0, v[6:7]
	global_store_dwordx4 v[6:7], v[2:5], off nt
	ds_read2_b32 v[6:7], v71 offset0:16 offset1:24
	ds_read2_b32 v[8:9], v71 offset0:49 offset1:57
	ds_read2_b32 v[10:11], v71 offset0:82 offset1:90
	ds_read2_b32 v[12:13], v71 offset0:115 offset1:123
	ds_read2_b32 v[14:15], v71 offset0:148 offset1:156
	ds_read2_b32 v[16:17], v71 offset0:181 offset1:189
	ds_read2_b32 v[18:19], v71 offset0:214 offset1:222
	ds_read2_b32 v[20:21], v71 offset0:247 offset1:255
	v_lshlrev_b64 v[22:23], 13, v[22:23]
	s_waitcnt lgkmcnt(6)
	v_cvt_pk_bf16_f32 v2, v6, v8
	s_waitcnt lgkmcnt(4)
	v_cvt_pk_bf16_f32 v3, v10, v12
	s_waitcnt lgkmcnt(2)
	v_cvt_pk_bf16_f32 v4, v14, v16
	s_waitcnt lgkmcnt(0)
	v_cvt_pk_bf16_f32 v5, v18, v20
	v_lshl_add_u64 v[22:23], v[0:1], 0, v[22:23]
	v_add_u32_e32 v6, s0, v38
	global_store_dwordx4 v[22:23], v[2:5], off nt
	s_mov_b64 s[0:1], 0
	s_nop 0
	v_cvt_pk_bf16_f32 v2, v7, v9
	v_ashrrev_i32_e32 v7, 31, v6
	v_lshlrev_b64 v[6:7], 13, v[6:7]
	v_cvt_pk_bf16_f32 v3, v11, v13
	v_cvt_pk_bf16_f32 v4, v15, v17
	v_cvt_pk_bf16_f32 v5, v19, v21
	v_lshl_add_u64 v[0:1], v[0:1], 0, v[6:7]
	global_store_dwordx4 v[0:1], v[2:5], off nt
	s_waitcnt lgkmcnt(0)
.LBB0_301:
	s_andn2_b64 vcc, exec, s[0:1]
	s_cbranch_vccnz .LBB0_311
	s_add_i32 s0, s36, 0xfe00
	s_lshr_b32 s0, s0, 1
	s_and_b32 s5, s0, 0x7fc0
	s_and_b32 s4, s4, 0xfe0
	v_or_b32_e32 v0, s4, v67
	v_add_u32_e32 v58, s5, v32
	v_lshlrev_b32_e32 v64, 2, v0
	v_ashrrev_i32_e32 v59, 31, v58
	v_lshl_add_u64 v[0:1], s[10:11], 0, v[64:65]
	v_lshlrev_b64 v[2:3], 14, v[58:59]
	v_lshl_add_u64 v[0:1], v[0:1], 0, v[2:3]
	s_mov_b32 s0, 0x20000
	v_add_co_u32_e32 v2, vcc, s0, v0
	s_mov_b32 s0, 0x40000
	s_nop 0
	v_addc_co_u32_e32 v3, vcc, 0, v1, vcc
	global_load_dwordx4 v[28:31], v[0:1], off nt
	global_load_dwordx4 v[24:27], v[2:3], off nt
	v_add_co_u32_e32 v2, vcc, s0, v0
	s_mov_b32 s0, 0x60000
	s_nop 0
	v_addc_co_u32_e32 v3, vcc, 0, v1, vcc
	v_add_co_u32_e32 v4, vcc, s0, v0
	s_mov_b32 s0, 0x80000
	s_nop 0
	v_addc_co_u32_e32 v5, vcc, 0, v1, vcc
	global_load_dwordx4 v[20:23], v[2:3], off nt
	global_load_dwordx4 v[16:19], v[4:5], off nt
	v_add_co_u32_e32 v2, vcc, s0, v0
	v_readlane_b32 s6, v251, 58
	s_nop 0
	v_addc_co_u32_e32 v3, vcc, 0, v1, vcc
	v_add_co_u32_e32 v4, vcc, 0xa0000, v0
	v_readlane_b32 s7, v251, 59
	s_nop 0
	v_addc_co_u32_e32 v5, vcc, 0, v1, vcc
	global_load_dwordx4 v[12:15], v[2:3], off nt
	global_load_dwordx4 v[8:11], v[4:5], off nt
	v_add_co_u32_e32 v2, vcc, 0xc0000, v0
	v_cndmask_b32_e64 v61, 0, 1, s[6:7]
	s_nop 0
	v_addc_co_u32_e32 v3, vcc, 0, v1, vcc
	v_add_co_u32_e32 v0, vcc, 0xe0000, v0
	v_mov_b32_e32 v60, 1.0
	s_nop 0
	v_addc_co_u32_e32 v1, vcc, 0, v1, vcc
	global_load_dwordx4 v[4:7], v[2:3], off nt
	s_nop 0
	global_load_dwordx4 v[0:3], v[0:1], off nt
	v_cmp_ne_u32_e64 s[0:1], 1, v61
	s_andn2_b64 vcc, exec, s[6:7]
	v_lshl_add_u64 v[58:59], v[58:59], 2, s[12:13]
	v_mov_b32_e32 v62, 1.0
	s_cbranch_vccnz .LBB0_304
	global_load_dword v62, v[58:59], off
	s_waitcnt vmcnt(0)
	v_pk_mul_f32 v[28:29], v[28:29], v[62:63] op_sel_hi:[1,0]
	v_pk_mul_f32 v[30:31], v[30:31], v[62:63] op_sel_hi:[1,0]
	global_load_dword v62, v[58:59], off offset:32

.LBB0_310:
	v_add_u32_e32 v8, 0x1080, v24
	ds_write2_b32 v8, v4, v5 offset1:1
	v_add_u32_e32 v4, 0x1088, v24
	ds_write2_b32 v4, v6, v7 offset1:1
	s_waitcnt vmcnt(0)
	v_pk_mul_f32 v[0:1], v[0:1], v[16:17] op_sel_hi:[1,0]
	v_add_u32_e32 v4, 0x14a0, v24
	ds_write2_b32 v4, v0, v1 offset1:1
	v_pk_mul_f32 v[0:1], v[2:3], v[16:17] op_sel_hi:[1,0]
	v_add_u32_e32 v2, 0x14a8, v24
	ds_write2_b32 v2, v0, v1 offset1:1
	s_waitcnt lgkmcnt(0)
	ds_read2_b32 v[6:7], v71 offset0:33 offset1:41
	ds_read2_b32 v[8:9], v71 offset1:8
	ds_read2_b32 v[10:11], v71 offset0:66 offset1:74
	ds_read2_b32 v[12:13], v71 offset0:99 offset1:107
	ds_read2_b32 v[14:15], v71 offset0:132 offset1:140
	ds_read2_b32 v[16:17], v71 offset0:165 offset1:173
	ds_read2_b32 v[18:19], v71 offset0:198 offset1:206
	ds_read2_b32 v[20:21], v71 offset0:231 offset1:239
	v_add_u32_e32 v22, s4, v32
	s_lshl_b32 s34, s5, 1
	v_ashrrev_i32_e32 v23, 31, v22
	v_lshl_add_u64 v[4:5], v[54:55], 0, s[34:35]
	v_lshlrev_b64 v[22:23], 11, v[22:23]
	s_waitcnt lgkmcnt(6)
	v_cvt_pk_bf16_f32 v0, v8, v6
	s_waitcnt lgkmcnt(4)
	v_cvt_pk_bf16_f32 v1, v10, v12
	s_waitcnt lgkmcnt(2)
	v_cvt_pk_bf16_f32 v2, v14, v16
	s_waitcnt lgkmcnt(0)
	v_cvt_pk_bf16_f32 v3, v18, v20
	v_lshl_add_u64 v[22:23], v[4:5], 0, v[22:23]
	v_add_u32_e32 v6, s4, v34
	global_store_dwordx4 v[22:23], v[0:3], off nt
	v_add_u32_e32 v22, s4, v36
	v_ashrrev_i32_e32 v23, 31, v22
	v_cvt_pk_bf16_f32 v0, v9, v7
	v_ashrrev_i32_e32 v7, 31, v6
	v_lshlrev_b64 v[6:7], 11, v[6:7]
	v_cvt_pk_bf16_f32 v1, v11, v13
	v_cvt_pk_bf16_f32 v2, v15, v17
	v_cvt_pk_bf16_f32 v3, v19, v21
	v_lshl_add_u64 v[6:7], v[4:5], 0, v[6:7]
	global_store_dwordx4 v[6:7], v[0:3], off nt
	ds_read2_b32 v[6:7], v71 offset0:16 offset1:24
	ds_read2_b32 v[8:9], v71 offset0:49 offset1:57
	ds_read2_b32 v[10:11], v71 offset0:82 offset1:90
	ds_read2_b32 v[12:13], v71 offset0:115 offset1:123
	ds_read2_b32 v[14:15], v71 offset0:148 offset1:156
	ds_read2_b32 v[16:17], v71 offset0:181 offset1:189
	ds_read2_b32 v[18:19], v71 offset0:214 offset1:222
	ds_read2_b32 v[20:21], v71 offset0:247 offset1:255
	v_lshlrev_b64 v[22:23], 11, v[22:23]
	s_waitcnt lgkmcnt(6)
	v_cvt_pk_bf16_f32 v0, v6, v8
	s_waitcnt lgkmcnt(4)
	v_cvt_pk_bf16_f32 v1, v10, v12
	s_waitcnt lgkmcnt(2)
	v_cvt_pk_bf16_f32 v2, v14, v16
	s_waitcnt lgkmcnt(0)
	v_cvt_pk_bf16_f32 v3, v18, v20
	v_lshl_add_u64 v[22:23], v[4:5], 0, v[22:23]
	v_add_u32_e32 v6, s4, v38
	global_store_dwordx4 v[22:23], v[0:3], off nt
	s_nop 1
	v_cvt_pk_bf16_f32 v0, v7, v9
	v_ashrrev_i32_e32 v7, 31, v6
	v_lshlrev_b64 v[6:7], 11, v[6:7]
	v_cvt_pk_bf16_f32 v1, v11, v13
	v_cvt_pk_bf16_f32 v2, v15, v17
	v_cvt_pk_bf16_f32 v3, v19, v21
	v_lshl_add_u64 v[4:5], v[4:5], 0, v[6:7]
	global_store_dwordx4 v[4:5], v[0:3], off nt
	s_waitcnt lgkmcnt(0)

.LBB0_312:
	s_andn2_b64 vcc, exec, s[0:1]
	s_cbranch_vccnz .LBB0_249
	s_ashr_i32 s0, s36, 31
	s_lshr_b32 s0, s0, 27
	s_add_i32 s0, s36, s0
	s_and_b32 s1, s0, 0xffffffe0
	s_sub_i32 s1, s36, s1
	s_lshl_b32 s0, s0, 1
	s_and_b32 s28, s0, 0xffffffc0
	s_lshl_b32 s4, s1, 5
	v_or_b32_e32 v64, s4, v67
	s_cmp_gt_i32 s1, -1
	s_cselect_b64 s[36:37], -1, 0
	s_cmp_lt_i32 s1, 0
	v_add_u32_e32 v60, s28, v32
	v_lshl_add_u64 v[58:59], v[64:65], 2, s[8:9]
	v_mov_b32_e32 v0, 0
	v_mov_b32_e32 v4, 0
	v_mov_b32_e32 v5, 0
	v_mov_b32_e32 v6, 0
	v_mov_b32_e32 v7, 0
	s_cbranch_scc1 .LBB0_315
	v_ashrrev_i32_e32 v61, 31, v60
	v_lshlrev_b64 v[2:3], 12, v[60:61]
	v_lshl_add_u64 v[2:3], v[58:59], 0, v[2:3]
	global_load_dwordx4 v[4:7], v[2:3], off nt
.LBB0_315:
	v_cndmask_b32_e64 v1, 0, 1, s[36:37]
	v_cmp_ne_u32_e64 s[0:1], 1, v1
	s_andn2_b64 vcc, exec, s[36:37]
	v_mov_b32_e32 v1, 0
	v_mov_b32_e32 v2, 0
	v_mov_b32_e32 v3, 0
	s_cbranch_vccnz .LBB0_317
	v_add_u32_e32 v0, 8, v60
	v_ashrrev_i32_e32 v1, 31, v0
	v_lshlrev_b64 v[0:1], 12, v[0:1]
	v_lshl_add_u64 v[0:1], v[58:59], 0, v[0:1]
	global_load_dwordx4 v[0:3], v[0:1], off nt
.LBB0_317:
	v_mov_b32_e32 v8, 0
	s_and_b64 vcc, exec, s[0:1]
	v_mov_b32_e32 v12, 0
	v_mov_b32_e32 v13, 0
	v_mov_b32_e32 v14, 0
	v_mov_b32_e32 v15, 0
	s_cbranch_vccnz .LBB0_319
	v_add_u32_e32 v10, 16, v60
	v_ashrrev_i32_e32 v11, 31, v10
	v_lshlrev_b64 v[10:11], 12, v[10:11]
	v_lshl_add_u64 v[10:11], v[58:59], 0, v[10:11]
	global_load_dwordx4 v[12:15], v[10:11], off nt
.LBB0_319:
	s_and_b64 vcc, exec, s[0:1]
	v_mov_b32_e32 v9, 0
	v_mov_b32_e32 v10, 0
	v_mov_b32_e32 v11, 0
	s_cbranch_vccnz .LBB0_321
	v_add_u32_e32 v8, 24, v60
	v_ashrrev_i32_e32 v9, 31, v8
	v_lshlrev_b64 v[8:9], 12, v[8:9]
	v_lshl_add_u64 v[8:9], v[58:59], 0, v[8:9]
	global_load_dwordx4 v[8:11], v[8:9], off nt
.LBB0_321:
	v_mov_b32_e32 v16, 0
	s_and_b64 vcc, exec, s[0:1]
	v_mov_b32_e32 v20, 0
	v_mov_b32_e32 v21, 0
	v_mov_b32_e32 v22, 0
	v_mov_b32_e32 v23, 0
	s_cbranch_vccnz .LBB0_323
	v_add_u32_e32 v18, 32, v60
	v_ashrrev_i32_e32 v19, 31, v18
	v_lshlrev_b64 v[18:19], 12, v[18:19]
	v_lshl_add_u64 v[18:19], v[58:59], 0, v[18:19]
	global_load_dwordx4 v[20:23], v[18:19], off nt
.LBB0_323:
	s_and_b64 vcc, exec, s[0:1]
	v_mov_b32_e32 v17, 0
	v_mov_b32_e32 v18, 0
	v_mov_b32_e32 v19, 0
	s_cbranch_vccnz .LBB0_325
	v_add_u32_e32 v16, 40, v60
	v_ashrrev_i32_e32 v17, 31, v16
	v_lshlrev_b64 v[16:17], 12, v[16:17]
	v_lshl_add_u64 v[16:17], v[58:59], 0, v[16:17]
	global_load_dwordx4 v[16:19], v[16:17], off nt
.LBB0_325:
	v_mov_b32_e32 v24, 0
	s_and_b64 vcc, exec, s[0:1]
	v_mov_b32_e32 v28, 0
	v_mov_b32_e32 v29, 0
	v_mov_b32_e32 v30, 0
	v_mov_b32_e32 v31, 0
	s_cbranch_vccnz .LBB0_327
	v_add_u32_e32 v26, 48, v60
	v_ashrrev_i32_e32 v27, 31, v26
	v_lshlrev_b64 v[26:27], 12, v[26:27]
	v_lshl_add_u64 v[26:27], v[58:59], 0, v[26:27]
	global_load_dwordx4 v[28:31], v[26:27], off nt
.LBB0_327:
	s_and_b64 vcc, exec, s[0:1]
	v_mov_b32_e32 v25, 0
	v_mov_b32_e32 v26, 0
	v_mov_b32_e32 v27, 0
	s_cbranch_vccnz .LBB0_248
	v_add_u32_e32 v24, 56, v60
	v_ashrrev_i32_e32 v25, 31, v24
	v_lshlrev_b64 v[24:25], 12, v[24:25]
	v_lshl_add_u64 v[24:25], v[58:59], 0, v[24:25]
	global_load_dwordx4 v[24:27], v[24:25], off nt
	s_branch .LBB0_248

.LBB0_338:
	v_add_u32_e32 v4, 0x1080, v24
	ds_write2_b32 v4, v12, v13 offset1:1
	v_add_u32_e32 v4, 0x1088, v24
	ds_write2_b32 v4, v10, v11 offset1:1
	s_waitcnt vmcnt(0)
	v_pk_mul_f32 v[0:1], v[0:1], v[8:9] op_sel_hi:[1,0]
	v_add_u32_e32 v4, 0x14a0, v24
	ds_write2_b32 v4, v0, v1 offset1:1
	v_pk_mul_f32 v[0:1], v[2:3], v[8:9] op_sel_hi:[1,0]
	v_add_u32_e32 v2, 0x14a8, v24
	ds_write2_b32 v2, v0, v1 offset1:1
	s_waitcnt lgkmcnt(0)
	ds_read2_b32 v[6:7], v71 offset0:33 offset1:41
	ds_read2_b32 v[8:9], v71 offset1:8
	ds_read2_b32 v[10:11], v71 offset0:66 offset1:74
	ds_read2_b32 v[12:13], v71 offset0:99 offset1:107
	ds_read2_b32 v[14:15], v71 offset0:132 offset1:140
	ds_read2_b32 v[16:17], v71 offset0:165 offset1:173
	ds_read2_b32 v[18:19], v71 offset0:198 offset1:206
	ds_read2_b32 v[20:21], v71 offset0:231 offset1:239
	v_add_u32_e32 v22, s4, v32
	v_ashrrev_i32_e32 v23, 31, v22
	v_lshl_add_u64 v[4:5], s[28:29], 1, v[50:51]
	v_lshlrev_b64 v[22:23], 11, v[22:23]
	s_waitcnt lgkmcnt(6)
	v_cvt_pk_bf16_f32 v0, v8, v6
	s_waitcnt lgkmcnt(4)
	v_cvt_pk_bf16_f32 v1, v10, v12
	s_waitcnt lgkmcnt(2)
	v_cvt_pk_bf16_f32 v2, v14, v16
	s_waitcnt lgkmcnt(0)
	v_cvt_pk_bf16_f32 v3, v18, v20
	v_lshl_add_u64 v[22:23], v[4:5], 0, v[22:23]
	v_add_u32_e32 v6, s4, v34
	global_store_dwordx4 v[22:23], v[0:3], off nt
	v_add_u32_e32 v22, s4, v36
	v_ashrrev_i32_e32 v23, 31, v22
	v_cvt_pk_bf16_f32 v0, v9, v7
	v_ashrrev_i32_e32 v7, 31, v6
	v_lshlrev_b64 v[6:7], 11, v[6:7]
	v_cvt_pk_bf16_f32 v1, v11, v13
	v_cvt_pk_bf16_f32 v2, v15, v17
	v_cvt_pk_bf16_f32 v3, v19, v21
	v_lshl_add_u64 v[6:7], v[4:5], 0, v[6:7]
	global_store_dwordx4 v[6:7], v[0:3], off nt
	ds_read2_b32 v[6:7], v71 offset0:16 offset1:24
	ds_read2_b32 v[8:9], v71 offset0:49 offset1:57
	ds_read2_b32 v[10:11], v71 offset0:82 offset1:90
	ds_read2_b32 v[12:13], v71 offset0:115 offset1:123
	ds_read2_b32 v[14:15], v71 offset0:148 offset1:156
	ds_read2_b32 v[16:17], v71 offset0:181 offset1:189
	ds_read2_b32 v[18:19], v71 offset0:214 offset1:222
	ds_read2_b32 v[20:21], v71 offset0:247 offset1:255
	v_lshlrev_b64 v[22:23], 11, v[22:23]
	s_waitcnt lgkmcnt(6)
	v_cvt_pk_bf16_f32 v0, v6, v8
	s_waitcnt lgkmcnt(4)
	v_cvt_pk_bf16_f32 v1, v10, v12
	s_waitcnt lgkmcnt(2)
	v_cvt_pk_bf16_f32 v2, v14, v16
	s_waitcnt lgkmcnt(0)
	v_cvt_pk_bf16_f32 v3, v18, v20
	v_lshl_add_u64 v[22:23], v[4:5], 0, v[22:23]
	v_add_u32_e32 v6, s4, v38
	global_store_dwordx4 v[22:23], v[0:3], off nt
	s_nop 1
	v_cvt_pk_bf16_f32 v0, v7, v9
	v_ashrrev_i32_e32 v7, 31, v6
	v_lshlrev_b64 v[6:7], 11, v[6:7]
	v_cvt_pk_bf16_f32 v1, v11, v13
	v_cvt_pk_bf16_f32 v2, v15, v17
	v_cvt_pk_bf16_f32 v3, v19, v21
	v_lshl_add_u64 v[4:5], v[4:5], 0, v[6:7]
	global_store_dwordx4 v[4:5], v[0:3], off nt
	s_waitcnt lgkmcnt(0)
	s_cbranch_execnz .LBB0_249
	s_branch .LBB0_298
